# K-loop: 4 of 16 LDS-DMA issues use SGPR-base + 32-bit VGPR offset form (drops 4 v_lshl_add_u64)
# speedup vs baseline: 1.0184x; 1.0048x over previous
.LBB0_386:
	s_add_i32 s71, s44, 2
	s_add_u32 s46, s0, 0x80
	s_addc_u32 s45, s1, 0
	s_add_i32 vcc_lo, 0, 0x10000
	s_cmp_eq_u32 s43, s44
	s_cselect_b32 s44, s72, s46
	s_cselect_b32 s45, s73, s45
	s_cselect_b32 s47, s75, s49
	s_cselect_b32 s46, s74, s48
	s_nop 0
	s_add_i32 m0, s98, 0xc000
	ds_read_b128 v[146:149], v229
	ds_read_b128 v[150:153], v229 offset:1024
	ds_read_b128 v[176:179], v229 offset:2048
	ds_read_b128 v[180:183], v229 offset:3072
	ds_read_b128 v[184:187], v229 offset:4096
	ds_read_b128 v[188:191], v229 offset:5120
	ds_read_b128 v[192:195], v229 offset:6144
	ds_read_b128 v[196:199], v229 offset:7168
	global_load_lds_dwordx4 v172, s[0:1]
	s_add_i32 m0, s98, 0xe000
	s_nop 0
	global_load_lds_dwordx4 v174, s[0:1]
	s_waitcnt lgkmcnt(8)
	s_barrier
	s_waitcnt lgkmcnt(0)
	v_mfma_f32_16x16x32_bf16 v[126:129], v[130:133], v[146:149], v[126:129]
	v_mfma_f32_16x16x32_bf16 v[122:125], v[138:141], v[146:149], v[122:125]
	v_mfma_f32_16x16x32_bf16 v[110:113], v[130:133], v[176:179], v[110:113]
	v_mfma_f32_16x16x32_bf16 v[106:109], v[138:141], v[176:179], v[106:109]
	v_mfma_f32_16x16x32_bf16 v[94:97], v[130:133], v[184:187], v[94:97]
	v_mfma_f32_16x16x32_bf16 v[90:93], v[138:141], v[184:187], v[90:93]
	v_mfma_f32_16x16x32_bf16 v[78:81], v[130:133], v[192:195], v[78:81]
	v_mfma_f32_16x16x32_bf16 v[74:77], v[138:141], v[192:195], v[74:77]
	v_mfma_f32_16x16x32_bf16 v[126:129], v[134:137], v[150:153], v[126:129]
	v_mfma_f32_16x16x32_bf16 v[122:125], v[142:145], v[150:153], v[122:125]
	v_mfma_f32_16x16x32_bf16 v[110:113], v[134:137], v[180:183], v[110:113]
	v_mfma_f32_16x16x32_bf16 v[106:109], v[142:145], v[180:183], v[106:109]
	v_mfma_f32_16x16x32_bf16 v[94:97], v[134:137], v[188:191], v[94:97]
	v_mfma_f32_16x16x32_bf16 v[90:93], v[142:145], v[188:191], v[90:93]
	v_mfma_f32_16x16x32_bf16 v[78:81], v[134:137], v[196:199], v[78:81]
	v_mfma_f32_16x16x32_bf16 v[74:77], v[142:145], v[196:199], v[74:77]
	s_barrier
	s_add_i32 vcc_hi, 0, 0x14000
	s_add_i32 vcc_lo, vcc_lo, s97
	v_add_u32_e32 v0, vcc_hi, v224
	v_lshl_add_u64 v[204:205], s[46:47], 0, v[158:159]
	s_mov_b32 m0, vcc_lo
	ds_read_b128 v[200:203], v0
	ds_read_b128 v[230:233], v0 offset:1024
	ds_read_b128 v[234:237], v0 offset:2048
	ds_read_b128 v[238:241], v0 offset:3072
	global_load_lds_dwordx4 v[204:205], off
	s_add_i32 m0, vcc_lo, 0x2000
	v_lshl_add_u64 v[242:243], s[46:47], 0, v[162:163]
	global_load_lds_dwordx4 v[242:243], off
	s_waitcnt vmcnt(6)
	s_barrier
	s_waitcnt lgkmcnt(0)
	v_mfma_f32_16x16x32_bf16 v[118:121], v[200:203], v[146:149], v[118:121]
	v_mfma_f32_16x16x32_bf16 v[114:117], v[234:237], v[146:149], v[114:117]
	v_mfma_f32_16x16x32_bf16 v[102:105], v[200:203], v[176:179], v[102:105]
	v_mfma_f32_16x16x32_bf16 v[98:101], v[234:237], v[176:179], v[98:101]
	v_mfma_f32_16x16x32_bf16 v[86:89], v[200:203], v[184:187], v[86:89]
	v_mfma_f32_16x16x32_bf16 v[82:85], v[234:237], v[184:187], v[82:85]
	v_mfma_f32_16x16x32_bf16 v[70:73], v[200:203], v[192:195], v[70:73]
	v_mfma_f32_16x16x32_bf16 v[66:69], v[234:237], v[192:195], v[66:69]
	v_mfma_f32_16x16x32_bf16 v[118:121], v[230:233], v[150:153], v[118:121]
	v_mfma_f32_16x16x32_bf16 v[114:117], v[238:241], v[150:153], v[114:117]
	v_mfma_f32_16x16x32_bf16 v[102:105], v[230:233], v[180:183], v[102:105]
	v_mfma_f32_16x16x32_bf16 v[98:101], v[238:241], v[180:183], v[98:101]
	v_mfma_f32_16x16x32_bf16 v[86:89], v[230:233], v[188:191], v[86:89]
	v_mfma_f32_16x16x32_bf16 v[82:85], v[238:241], v[188:191], v[82:85]
	v_mfma_f32_16x16x32_bf16 v[70:73], v[230:233], v[196:199], v[70:73]
	v_mfma_f32_16x16x32_bf16 v[66:69], v[238:241], v[196:199], v[66:69]
	s_barrier
	s_mov_b32 m0, s98
	v_lshl_add_u64 v[244:245], s[44:45], 0, v[156:157]
	ds_read_b128 v[146:149], v229 offset:16384
	ds_read_b128 v[150:153], v229 offset:17408
	ds_read_b128 v[176:179], v229 offset:18432
	ds_read_b128 v[180:183], v229 offset:19456
	ds_read_b128 v[184:187], v229 offset:20480
	ds_read_b128 v[188:191], v229 offset:21504
	ds_read_b128 v[192:195], v229 offset:22528
	ds_read_b128 v[196:199], v229 offset:23552
	global_load_lds_dwordx4 v[244:245], off
	s_mov_b32 m0, s99
	v_lshl_add_u64 v[246:247], s[44:45], 0, v[160:161]
	global_load_lds_dwordx4 v[246:247], off
	s_barrier
	s_waitcnt lgkmcnt(0)
	v_mfma_f32_16x16x32_bf16 v[62:65], v[130:133], v[146:149], v[62:65]
	v_mfma_f32_16x16x32_bf16 v[58:61], v[138:141], v[146:149], v[58:61]
	v_mfma_f32_16x16x32_bf16 v[46:49], v[130:133], v[176:179], v[46:49]
	v_mfma_f32_16x16x32_bf16 v[42:45], v[138:141], v[176:179], v[42:45]
	v_mfma_f32_16x16x32_bf16 v[30:33], v[130:133], v[184:187], v[30:33]
	v_mfma_f32_16x16x32_bf16 v[26:29], v[138:141], v[184:187], v[26:29]
	v_mfma_f32_16x16x32_bf16 v[14:17], v[130:133], v[192:195], v[14:17]
	v_mfma_f32_16x16x32_bf16 v[10:13], v[138:141], v[192:195], v[10:13]
	v_mfma_f32_16x16x32_bf16 v[62:65], v[134:137], v[150:153], v[62:65]
	v_mfma_f32_16x16x32_bf16 v[58:61], v[142:145], v[150:153], v[58:61]
	v_mfma_f32_16x16x32_bf16 v[46:49], v[134:137], v[180:183], v[46:49]
	v_mfma_f32_16x16x32_bf16 v[42:45], v[142:145], v[180:183], v[42:45]
	v_mfma_f32_16x16x32_bf16 v[30:33], v[134:137], v[188:191], v[30:33]
	v_mfma_f32_16x16x32_bf16 v[26:29], v[142:145], v[188:191], v[26:29]
	v_mfma_f32_16x16x32_bf16 v[14:17], v[134:137], v[196:199], v[14:17]
	v_mfma_f32_16x16x32_bf16 v[10:13], v[142:145], v[196:199], v[10:13]
	s_barrier
	s_add_u32 s46, s46, s95
	s_addc_u32 s47, s47, 0
	s_add_i32 vcc_lo, vcc_hi, s97
	v_lshl_add_u64 v[248:249], s[46:47], 0, v[158:159]
	s_mov_b32 m0, vcc_lo
	v_lshl_add_u64 v[250:251], s[46:47], 0, v[162:163]
	global_load_lds_dwordx4 v[248:249], off
	s_add_i32 m0, vcc_lo, 0x2000
	s_nop 0
	global_load_lds_dwordx4 v[250:251], off
	v_add_u32_e32 v0, 0x18000, v224
	ds_read_b128 v[130:133], v0
	ds_read_b128 v[134:137], v0 offset:1024
	ds_read_b128 v[138:141], v0 offset:2048
	ds_read_b128 v[142:145], v0 offset:3072
	s_waitcnt vmcnt(6)
	s_barrier
	v_mfma_f32_16x16x32_bf16 v[54:57], v[200:203], v[146:149], v[54:57]
	v_mfma_f32_16x16x32_bf16 v[50:53], v[234:237], v[146:149], v[50:53]
	v_mfma_f32_16x16x32_bf16 v[38:41], v[200:203], v[176:179], v[38:41]
	v_mfma_f32_16x16x32_bf16 v[34:37], v[234:237], v[176:179], v[34:37]
	v_mfma_f32_16x16x32_bf16 v[22:25], v[200:203], v[184:187], v[22:25]
	v_mfma_f32_16x16x32_bf16 v[18:21], v[234:237], v[184:187], v[18:21]
	v_mfma_f32_16x16x32_bf16 v[6:9], v[200:203], v[192:195], v[6:9]
	v_mfma_f32_16x16x32_bf16 v[2:5], v[234:237], v[192:195], v[2:5]
	v_mfma_f32_16x16x32_bf16 v[54:57], v[230:233], v[150:153], v[54:57]
	v_mfma_f32_16x16x32_bf16 v[50:53], v[238:241], v[150:153], v[50:53]
	v_mfma_f32_16x16x32_bf16 v[38:41], v[230:233], v[180:183], v[38:41]
	v_mfma_f32_16x16x32_bf16 v[34:37], v[238:241], v[180:183], v[34:37]
	v_mfma_f32_16x16x32_bf16 v[22:25], v[230:233], v[188:191], v[22:25]
	v_mfma_f32_16x16x32_bf16 v[18:21], v[238:241], v[188:191], v[18:21]
	v_mfma_f32_16x16x32_bf16 v[6:9], v[230:233], v[196:199], v[6:9]
	v_mfma_f32_16x16x32_bf16 v[2:5], v[238:241], v[196:199], v[2:5]
	s_barrier
	s_add_i32 s46, 0, 0x18000
	s_add_u32 s44, s44, s20
	s_addc_u32 s45, s45, 0
	s_mov_b32 m0, s94
	s_nop 0
	ds_read_b128 v[146:149], v229 offset:32768
	ds_read_b128 v[150:153], v229 offset:33792
	ds_read_b128 v[176:179], v229 offset:34816
	ds_read_b128 v[180:183], v229 offset:35840
	ds_read_b128 v[184:187], v229 offset:36864
	ds_read_b128 v[188:191], v229 offset:37888
	ds_read_b128 v[192:195], v229 offset:38912
	ds_read_b128 v[196:199], v229 offset:39936
	global_load_lds_dwordx4 v156, s[44:45]
	s_mov_b32 m0, s65
	s_nop 0
	global_load_lds_dwordx4 v160, s[44:45]
	s_waitcnt lgkmcnt(8)
	s_barrier
	s_waitcnt lgkmcnt(0)
	v_mfma_f32_16x16x32_bf16 v[126:129], v[130:133], v[146:149], v[126:129]
	v_mfma_f32_16x16x32_bf16 v[122:125], v[138:141], v[146:149], v[122:125]
	v_mfma_f32_16x16x32_bf16 v[110:113], v[130:133], v[176:179], v[110:113]
	v_mfma_f32_16x16x32_bf16 v[106:109], v[138:141], v[176:179], v[106:109]
	v_mfma_f32_16x16x32_bf16 v[94:97], v[130:133], v[184:187], v[94:97]
	v_mfma_f32_16x16x32_bf16 v[90:93], v[138:141], v[184:187], v[90:93]
	v_mfma_f32_16x16x32_bf16 v[78:81], v[130:133], v[192:195], v[78:81]
	v_mfma_f32_16x16x32_bf16 v[74:77], v[138:141], v[192:195], v[74:77]
	v_mfma_f32_16x16x32_bf16 v[126:129], v[134:137], v[150:153], v[126:129]
	v_mfma_f32_16x16x32_bf16 v[122:125], v[142:145], v[150:153], v[122:125]
	v_mfma_f32_16x16x32_bf16 v[110:113], v[134:137], v[180:183], v[110:113]
	v_mfma_f32_16x16x32_bf16 v[106:109], v[142:145], v[180:183], v[106:109]
	v_mfma_f32_16x16x32_bf16 v[94:97], v[134:137], v[188:191], v[94:97]
	v_mfma_f32_16x16x32_bf16 v[90:93], v[142:145], v[188:191], v[90:93]
	v_mfma_f32_16x16x32_bf16 v[78:81], v[134:137], v[196:199], v[78:81]
	v_mfma_f32_16x16x32_bf16 v[74:77], v[142:145], v[196:199], v[74:77]
	s_barrier
	s_add_i32 s44, 0, 0x1c000
	s_add_i32 s45, s46, s97
	v_add_u32_e32 v0, s44, v224
	v_lshl_add_u64 v[204:205], v[204:205], 0, s[22:23]
	s_mov_b32 m0, s45
	ds_read_b128 v[200:203], v0
	ds_read_b128 v[230:233], v0 offset:1024
	ds_read_b128 v[234:237], v0 offset:2048
	ds_read_b128 v[238:241], v0 offset:3072
	global_load_lds_dwordx4 v[204:205], off
	s_add_i32 m0, s45, 0x2000
	v_lshl_add_u64 v[204:205], v[242:243], 0, s[22:23]
	global_load_lds_dwordx4 v[204:205], off
	s_waitcnt vmcnt(6)
	s_barrier
	s_waitcnt lgkmcnt(0)
	v_mfma_f32_16x16x32_bf16 v[118:121], v[200:203], v[146:149], v[118:121]
	v_mfma_f32_16x16x32_bf16 v[114:117], v[234:237], v[146:149], v[114:117]
	v_mfma_f32_16x16x32_bf16 v[102:105], v[200:203], v[176:179], v[102:105]
	v_mfma_f32_16x16x32_bf16 v[98:101], v[234:237], v[176:179], v[98:101]
	v_mfma_f32_16x16x32_bf16 v[86:89], v[200:203], v[184:187], v[86:89]
	v_mfma_f32_16x16x32_bf16 v[82:85], v[234:237], v[184:187], v[82:85]
	v_mfma_f32_16x16x32_bf16 v[70:73], v[200:203], v[192:195], v[70:73]
	v_mfma_f32_16x16x32_bf16 v[66:69], v[234:237], v[192:195], v[66:69]
	v_mfma_f32_16x16x32_bf16 v[118:121], v[230:233], v[150:153], v[118:121]
	v_mfma_f32_16x16x32_bf16 v[114:117], v[238:241], v[150:153], v[114:117]
	v_mfma_f32_16x16x32_bf16 v[102:105], v[230:233], v[180:183], v[102:105]
	v_mfma_f32_16x16x32_bf16 v[98:101], v[238:241], v[180:183], v[98:101]
	v_mfma_f32_16x16x32_bf16 v[86:89], v[230:233], v[188:191], v[86:89]
	v_mfma_f32_16x16x32_bf16 v[82:85], v[238:241], v[188:191], v[82:85]
	v_mfma_f32_16x16x32_bf16 v[70:73], v[230:233], v[196:199], v[70:73]
	v_mfma_f32_16x16x32_bf16 v[66:69], v[238:241], v[196:199], v[66:69]
	s_barrier
	s_mov_b32 m0, s87
	v_lshl_add_u64 v[204:205], v[244:245], 0, s[22:23]
	ds_read_b128 v[146:149], v229 offset:49152
	ds_read_b128 v[150:153], v229 offset:50176
	ds_read_b128 v[176:179], v229 offset:51200
	ds_read_b128 v[180:183], v229 offset:52224
	ds_read_b128 v[184:187], v229 offset:53248
	ds_read_b128 v[188:191], v229 offset:54272
	ds_read_b128 v[192:195], v229 offset:55296
	ds_read_b128 v[196:199], v229 offset:56320
	global_load_lds_dwordx4 v[204:205], off
	s_mov_b32 m0, s29
	v_lshl_add_u64 v[204:205], v[246:247], 0, s[22:23]
	global_load_lds_dwordx4 v[204:205], off
	s_barrier
	s_waitcnt lgkmcnt(0)
	v_mfma_f32_16x16x32_bf16 v[62:65], v[130:133], v[146:149], v[62:65]
	v_mfma_f32_16x16x32_bf16 v[58:61], v[138:141], v[146:149], v[58:61]
	v_mfma_f32_16x16x32_bf16 v[46:49], v[130:133], v[176:179], v[46:49]
	v_mfma_f32_16x16x32_bf16 v[42:45], v[138:141], v[176:179], v[42:45]
	v_mfma_f32_16x16x32_bf16 v[30:33], v[130:133], v[184:187], v[30:33]
	v_mfma_f32_16x16x32_bf16 v[26:29], v[138:141], v[184:187], v[26:29]
	v_mfma_f32_16x16x32_bf16 v[14:17], v[130:133], v[192:195], v[14:17]
	v_mfma_f32_16x16x32_bf16 v[10:13], v[138:141], v[192:195], v[10:13]
	v_mfma_f32_16x16x32_bf16 v[62:65], v[134:137], v[150:153], v[62:65]
	v_mfma_f32_16x16x32_bf16 v[58:61], v[142:145], v[150:153], v[58:61]
	v_mfma_f32_16x16x32_bf16 v[46:49], v[134:137], v[180:183], v[46:49]
	v_mfma_f32_16x16x32_bf16 v[42:45], v[142:145], v[180:183], v[42:45]
	v_mfma_f32_16x16x32_bf16 v[30:33], v[134:137], v[188:191], v[30:33]
	v_mfma_f32_16x16x32_bf16 v[26:29], v[142:145], v[188:191], v[26:29]
	v_mfma_f32_16x16x32_bf16 v[14:17], v[134:137], v[196:199], v[14:17]
	v_mfma_f32_16x16x32_bf16 v[10:13], v[142:145], v[196:199], v[10:13]
	s_barrier
	s_add_i32 s44, s44, s97
	s_mov_b32 m0, s44
	v_lshl_add_u64 v[130:131], v[248:249], 0, s[22:23]
	global_load_lds_dwordx4 v[130:131], off
	s_add_i32 m0, s44, 0x2000
	v_lshl_add_u64 v[130:131], v[250:251], 0, s[22:23]
	global_load_lds_dwordx4 v[130:131], off
	v_add_u32_e32 v0, 0x10000, v224
	ds_read_b128 v[130:133], v0
	ds_read_b128 v[134:137], v0 offset:1024
	ds_read_b128 v[138:141], v0 offset:2048
	ds_read_b128 v[142:145], v0 offset:3072
	s_add_u32 s0, s0, 0x100
	s_addc_u32 s1, s1, 0
	s_add_u32 s48, s48, 0x100
	s_addc_u32 s49, s49, 0
	s_cmp_ge_i32 s71, s6
	s_mov_b32 s44, s71
	s_waitcnt vmcnt(6)
	s_barrier
	v_mfma_f32_16x16x32_bf16 v[54:57], v[200:203], v[146:149], v[54:57]
	v_mfma_f32_16x16x32_bf16 v[50:53], v[234:237], v[146:149], v[50:53]
	v_mfma_f32_16x16x32_bf16 v[38:41], v[200:203], v[176:179], v[38:41]
	v_mfma_f32_16x16x32_bf16 v[34:37], v[234:237], v[176:179], v[34:37]
	v_mfma_f32_16x16x32_bf16 v[22:25], v[200:203], v[184:187], v[22:25]
	v_mfma_f32_16x16x32_bf16 v[18:21], v[234:237], v[184:187], v[18:21]
	v_mfma_f32_16x16x32_bf16 v[6:9], v[200:203], v[192:195], v[6:9]
	v_mfma_f32_16x16x32_bf16 v[2:5], v[234:237], v[192:195], v[2:5]
	v_mfma_f32_16x16x32_bf16 v[54:57], v[230:233], v[150:153], v[54:57]
	v_mfma_f32_16x16x32_bf16 v[50:53], v[238:241], v[150:153], v[50:53]
	v_mfma_f32_16x16x32_bf16 v[38:41], v[230:233], v[180:183], v[38:41]
	v_mfma_f32_16x16x32_bf16 v[34:37], v[238:241], v[180:183], v[34:37]
	v_mfma_f32_16x16x32_bf16 v[22:25], v[230:233], v[188:191], v[22:25]
	v_mfma_f32_16x16x32_bf16 v[18:21], v[238:241], v[188:191], v[18:21]
	v_mfma_f32_16x16x32_bf16 v[6:9], v[230:233], v[196:199], v[6:9]
	v_mfma_f32_16x16x32_bf16 v[2:5], v[238:241], v[196:199], v[2:5]
	s_barrier
	s_cbranch_scc0 .LBB0_386
	s_lshl_b32 s46, s77, 8
	s_cmp_lt_i32 s64, 1
	s_mov_b64 s[0:1], -1
	s_cbranch_scc1 .LBB0_403
